# attention PV phase: V fragment LDS reads software-pipelined 3 steps ahead over 4 register buffers
# speedup vs baseline: 1.0246x; 1.0019x over previous
; __device__ __forceinline__ unsigned pk2(float lo, float hi) { return pg8::cvt_pk_bf16(lo, hi); }
; __device__ __forceinline__ void attn_unit(const bf16* proj, unsigned char* ws, LAS unsigned char* lds, int a) {
;     ...
;             const float mnew = fmaxf(mrow[rt], mx), alpha = __builtin_amdgcn_exp2f(mrow[rt] - mnew);
;             mrow[rt] = mnew; float ls = lrow[rt] * alpha;
; #pragma unroll
;             for (int dt = 0; dt < 8; ++dt) O[rt][dt] *= alpha;
; #pragma unroll
;             for (int kt = 0; kt < 8; ++kt)
; #pragma unroll
;                 for (int r = 0; r < 4; ++r) { const float p = __builtin_amdgcn_exp2f(st[rt][kt][r] - mnew); st[rt][kt][r] = p; ls += p; }
;             lrow[rt] = ls;
; #pragma unroll
;             for (int tp = 0; tp < 4; ++tp) {
;                 v4u w; w.x = pk2(st[rt][2 * tp][0], st[rt][2 * tp][1]); w.y = pk2(st[rt][2 * tp][2], st[rt][2 * tp][3]);
;                 w.z = pk2(st[rt][2 * tp + 1][0], st[rt][2 * tp + 1][1]); w.w = pk2(st[rt][2 * tp + 1][2], st[rt][2 * tp + 1][3]);
;                 pb[rt][tp] = __builtin_bit_cast(bf16x8, w);
;             }
.LBB0_612:
	v_sub_f32_e32 v209, v209, v207
	v_exp_f32_e32 v210, v209
	s_add_i32 s70, s70, 1
	s_addk_i32 s51, 0x80
	s_and_b64 vcc, exec, s[54:55]
	v_fmac_f32_e32 v238, v179, v210
	v_add_f32_e32 v179, v239, v238
	v_add_f32_e32 v179, v240, v179
	v_add_f32_e32 v179, v241, v179
	v_add_f32_e32 v179, v242, v179
	v_add_f32_e32 v179, v243, v179
	v_add_f32_e32 v179, v244, v179
	v_add_f32_e32 v179, v245, v179
	v_add_f32_e32 v179, v246, v179
	v_add_f32_e32 v179, v247, v179
	v_add_f32_e32 v179, v248, v179
	v_add_f32_e32 v179, v249, v179
	v_add_f32_e32 v179, v250, v179
	v_add_f32_e32 v179, v251, v179
	v_add_f32_e32 v179, v252, v179
	v_add_f32_e32 v179, v253, v179
	v_add_f32_e32 v144, v144, v179
	v_add_f32_e32 v144, v145, v144
	v_add_f32_e32 v144, v146, v144
	v_add_f32_e32 v144, v147, v144
	v_add_f32_e32 v144, v148, v144
	v_add_f32_e32 v144, v149, v144
	v_add_f32_e32 v144, v150, v144
	v_add_f32_e32 v144, v151, v144
	v_add_f32_e32 v144, v152, v144
	v_add_f32_e32 v144, v153, v144
	v_add_f32_e32 v144, v154, v144
	v_add_f32_e32 v144, v155, v144
	v_add_f32_e32 v144, v156, v144
	v_add_f32_e32 v144, v157, v144
	v_add_f32_e32 v144, v158, v144
	v_add_f32_e32 v179, v159, v144
	v_max3_f32 v144, v140, s67, v141
	v_max3_f32 v144, v144, v142, v143
	v_max3_f32 v144, v144, v136, v137
	v_max3_f32 v144, v144, v138, v139
	v_max3_f32 v144, v144, v132, v133
	v_max3_f32 v144, v144, v134, v135
	v_max3_f32 v144, v144, v128, v129
	v_max3_f32 v144, v144, v130, v131
	v_max3_f32 v144, v144, v124, v125
	v_max3_f32 v144, v144, v126, v127
	v_max3_f32 v144, v144, v120, v121
	v_max3_f32 v144, v144, v122, v123
	v_max3_f32 v144, v144, v116, v117
	v_max3_f32 v144, v144, v118, v119
	v_max3_f32 v144, v144, v112, v113
	v_max3_f32 v144, v144, v114, v115
	ds_bpermute_b32 v145, v203, v144
	v_pk_mul_f32 v[66:67], v[66:67], v[210:211] op_sel_hi:[1,0]
	v_pk_mul_f32 v[64:65], v[64:65], v[210:211] op_sel_hi:[1,0]
	v_pk_mul_f32 v[62:63], v[62:63], v[210:211] op_sel_hi:[1,0]
	v_pk_mul_f32 v[60:61], v[60:61], v[210:211] op_sel_hi:[1,0]
	s_waitcnt lgkmcnt(0)
	v_max_f32_e32 v145, v145, v145
	v_max_f32_e32 v144, v144, v145
	ds_bpermute_b32 v145, v204, v144
	v_pk_mul_f32 v[70:71], v[70:71], v[210:211] op_sel_hi:[1,0]
	v_pk_mul_f32 v[68:69], v[68:69], v[210:211] op_sel_hi:[1,0]
	v_pk_mul_f32 v[74:75], v[74:75], v[210:211] op_sel_hi:[1,0]
	v_pk_mul_f32 v[72:73], v[72:73], v[210:211] op_sel_hi:[1,0]
	s_waitcnt lgkmcnt(0)
	v_max3_f32 v148, v208, v144, v145
	v_sub_f32_e32 v144, v208, v148
	v_exp_f32_e32 v150, v144
	v_sub_f32_e32 v136, v136, v148
	v_exp_f32_e32 v136, v136
	v_sub_f32_e32 v137, v137, v148
	v_pk_mul_f32 v[144:145], v[84:85], v[150:151] op_sel_hi:[1,0]
	v_sub_f32_e32 v84, v140, v148
	v_pk_mul_f32 v[146:147], v[86:87], v[150:151] op_sel_hi:[1,0]
	v_exp_f32_e32 v84, v84
	v_sub_f32_e32 v86, v141, v148
	v_exp_f32_e32 v86, v86
	v_sub_f32_e32 v87, v142, v148
	v_exp_f32_e32 v87, v87
	v_sub_f32_e32 v140, v143, v148
	v_exp_f32_e32 v140, v140
	v_fma_f32 v85, v176, v150, v84
	v_add_f32_e32 v85, v86, v85
	v_exp_f32_e32 v137, v137
	v_sub_f32_e32 v138, v138, v148
	v_add_f32_e32 v85, v87, v85
	v_exp_f32_e32 v138, v138
	v_sub_f32_e32 v139, v139, v148
	v_add_f32_e32 v85, v140, v85
	v_exp_f32_e32 v139, v139
	v_sub_f32_e32 v132, v132, v148
	v_add_f32_e32 v85, v136, v85
	v_exp_f32_e32 v132, v132
	v_sub_f32_e32 v133, v133, v148
	v_add_f32_e32 v85, v137, v85
	v_exp_f32_e32 v133, v133
	v_sub_f32_e32 v134, v134, v148
	v_add_f32_e32 v85, v138, v85
	v_exp_f32_e32 v134, v134
	v_sub_f32_e32 v135, v135, v148
	v_add_f32_e32 v85, v139, v85
	v_exp_f32_e32 v135, v135
	v_sub_f32_e32 v128, v128, v148
	v_add_f32_e32 v85, v132, v85
	v_exp_f32_e32 v128, v128
	v_sub_f32_e32 v129, v129, v148
	v_add_f32_e32 v85, v133, v85
	v_exp_f32_e32 v129, v129
	v_sub_f32_e32 v130, v130, v148
	v_add_f32_e32 v85, v134, v85
	v_exp_f32_e32 v130, v130
	v_sub_f32_e32 v131, v131, v148
	v_add_f32_e32 v85, v135, v85
	v_exp_f32_e32 v131, v131
	v_sub_f32_e32 v124, v124, v148
	v_add_f32_e32 v85, v128, v85
	v_exp_f32_e32 v124, v124
	v_sub_f32_e32 v125, v125, v148
	v_add_f32_e32 v85, v129, v85
	v_exp_f32_e32 v125, v125
	v_sub_f32_e32 v126, v126, v148
	v_add_f32_e32 v85, v130, v85
	v_exp_f32_e32 v126, v126
	v_sub_f32_e32 v127, v127, v148
	v_add_f32_e32 v85, v131, v85
	v_exp_f32_e32 v127, v127
	v_sub_f32_e32 v120, v120, v148
	v_add_f32_e32 v85, v124, v85
	v_exp_f32_e32 v141, v120
	v_sub_f32_e32 v120, v121, v148
	v_add_f32_e32 v85, v125, v85
	v_exp_f32_e32 v142, v120
	v_sub_f32_e32 v120, v122, v148
	v_add_f32_e32 v85, v126, v85
	v_exp_f32_e32 v143, v120
	v_sub_f32_e32 v120, v123, v148
	v_add_f32_e32 v85, v127, v85
	v_exp_f32_e32 v149, v120
	v_sub_f32_e32 v116, v116, v148
	v_pk_mul_f32 v[38:39], v[38:39], v[150:151] op_sel_hi:[1,0]
	v_pk_mul_f32 v[36:37], v[36:37], v[150:151] op_sel_hi:[1,0]
	v_pk_mul_f32 v[34:35], v[34:35], v[150:151] op_sel_hi:[1,0]
	v_pk_mul_f32 v[32:33], v[32:33], v[150:151] op_sel_hi:[1,0]
	v_pk_mul_f32 v[42:43], v[42:43], v[150:151] op_sel_hi:[1,0]
	v_pk_mul_f32 v[40:41], v[40:41], v[150:151] op_sel_hi:[1,0]
	v_pk_mul_f32 v[46:47], v[46:47], v[150:151] op_sel_hi:[1,0]
	v_pk_mul_f32 v[44:45], v[44:45], v[150:151] op_sel_hi:[1,0]
	v_pk_mul_f32 v[50:51], v[50:51], v[150:151] op_sel_hi:[1,0]
	v_pk_mul_f32 v[48:49], v[48:49], v[150:151] op_sel_hi:[1,0]
	v_pk_mul_f32 v[54:55], v[54:55], v[150:151] op_sel_hi:[1,0]
	v_pk_mul_f32 v[52:53], v[52:53], v[150:151] op_sel_hi:[1,0]
	v_pk_mul_f32 v[58:59], v[58:59], v[150:151] op_sel_hi:[1,0]
	v_pk_mul_f32 v[56:57], v[56:57], v[150:151] op_sel_hi:[1,0]
	v_add_f32_e32 v85, v141, v85
	v_exp_f32_e32 v150, v116
	v_sub_f32_e32 v116, v117, v148
	v_add_f32_e32 v85, v142, v85
	v_exp_f32_e32 v151, v116
; #define LAS __attribute__((address_space(3)))
; __device__ __forceinline__ unsigned pk2(float lo, float hi) { return pg8::cvt_pk_bf16(lo, hi); }
; __device__ __forceinline__ void attn_unit(const bf16* proj, unsigned char* ws, LAS unsigned char* lds, int a) {
;     ...
;             mrow[rt] = mnew; float ls = lrow[rt] * alpha;
; #pragma unroll
;             for (int dt = 0; dt < 8; ++dt) O[rt][dt] *= alpha;
; #pragma unroll
;             for (int kt = 0; kt < 8; ++kt)
; #pragma unroll
;                 for (int r = 0; r < 4; ++r) { const float p = __builtin_amdgcn_exp2f(st[rt][kt][r] - mnew); st[rt][kt][r] = p; ls += p; }
;             lrow[rt] = ls;
; #pragma unroll
;             for (int tp = 0; tp < 4; ++tp) {
;                 v4u w; w.x = pk2(st[rt][2 * tp][0], st[rt][2 * tp][1]); w.y = pk2(st[rt][2 * tp][2], st[rt][2 * tp][3]);
;                 w.z = pk2(st[rt][2 * tp + 1][0], st[rt][2 * tp + 1][1]); w.w = pk2(st[rt][2 * tp + 1][2], st[rt][2 * tp + 1][3]);
;                 pb[rt][tp] = __builtin_bit_cast(bf16x8, w);
;             }
;         }
; #pragma unroll
;         for (int dt = 0; dt < 8; ++dt)
; #pragma unroll
;             for (int tp = 0; tp < 4; ++tp) {
;                 const LAS unsigned char* p0 = VS + (32 * tp + 4 * fq + (fr >> 2)) * V_STRIDE + (16 * dt + 4 * (fr & 3)) * 2;
;                 const bf16x8 vf = tr_frag(p0, p0 + 16 * V_STRIDE);
;                 O[0][dt] = __builtin_amdgcn_mfma_f32_16x16x32_bf16(vf, pb[0][tp], O[0][dt], 0, 0, 0);
;                 O[1][dt] = __builtin_amdgcn_mfma_f32_16x16x32_bf16(vf, pb[1][tp], O[1][dt], 0, 0, 0);
;             }
	v_sub_f32_e32 v116, v118, v148
	v_add_f32_e32 v85, v143, v85
	v_exp_f32_e32 v152, v116
	v_sub_f32_e32 v116, v119, v148
	v_add_f32_e32 v85, v149, v85
	v_exp_f32_e32 v153, v116
	v_sub_f32_e32 v112, v112, v148
	v_add_f32_e32 v85, v150, v85
	v_exp_f32_e32 v154, v112
	v_sub_f32_e32 v112, v113, v148
	v_add_f32_e32 v85, v151, v85
	v_exp_f32_e32 v155, v112
	v_sub_f32_e32 v112, v114, v148
	v_add_f32_e32 v85, v152, v85
	v_exp_f32_e32 v156, v112
	v_sub_f32_e32 v112, v115, v148
	v_add_f32_e32 v85, v153, v85
	v_exp_f32_e32 v157, v112
	v_add_f32_e32 v85, v154, v85
	v_add_f32_e32 v85, v155, v85
	v_add_f32_e32 v85, v156, v85
	v_add_f32_e32 v176, v157, v85
	v_cvt_pk_bf16_f32 v120, v84, v86
	v_cvt_pk_bf16_f32 v121, v87, v140
	v_cvt_pk_bf16_f32 v122, v136, v137
	v_cvt_pk_bf16_f32 v123, v138, v139
	v_cvt_pk_bf16_f32 v116, v132, v133
	v_cvt_pk_bf16_f32 v117, v134, v135
	v_cvt_pk_bf16_f32 v118, v128, v129
	v_cvt_pk_bf16_f32 v119, v130, v131
	v_cvt_pk_bf16_f32 v112, v124, v125
	v_cvt_pk_bf16_f32 v113, v126, v127
	v_cvt_pk_bf16_f32 v114, v141, v142
	v_cvt_pk_bf16_f32 v115, v143, v149
	v_cvt_pk_bf16_f32 v84, v150, v151
	v_cvt_pk_bf16_f32 v85, v152, v153
	v_cvt_pk_bf16_f32 v86, v154, v155
	v_cvt_pk_bf16_f32 v87, v156, v157
	ds_read_b64_tr_b16 v[124:125], v202
	ds_read_b64_tr_b16 v[126:127], v202 offset:4608
	ds_read_b64_tr_b16 v[128:129], v202 offset:9216
	ds_read_b64_tr_b16 v[130:131], v202 offset:13824
	ds_read_b64_tr_b16 v[132:133], v202 offset:18432
	ds_read_b64_tr_b16 v[134:135], v202 offset:23040
	v_mul_f32_e64 v78, v78, v210
	v_mul_f32_e64 v79, v79, v210
	v_pk_mul_f32 v[76:77], v[76:77], v[210:211] op_sel_hi:[1,0]
	v_pk_mul_f32 v[82:83], v[82:83], v[210:211] op_sel_hi:[1,0]
	v_pk_mul_f32 v[80:81], v[80:81], v[210:211] op_sel_hi:[1,0]
	v_pk_mul_f32 v[90:91], v[90:91], v[210:211] op_sel_hi:[1,0]
	v_mul_f32_e64 v88, v88, v210
	v_mul_f32_e64 v89, v89, v210
	v_pk_mul_f32 v[98:99], v[98:99], v[210:211] op_sel_hi:[1,0]
	v_pk_mul_f32 v[96:97], v[96:97], v[210:211] op_sel_hi:[1,0]
	ds_read_b64_tr_b16 v[136:137], v202 offset:27648
	ds_read_b64_tr_b16 v[138:139], v202 offset:32256
	s_waitcnt lgkmcnt(6)
	v_mfma_f32_16x16x32_bf16 v[64:67], v[124:127], v[108:111], v[64:67]
	v_mfma_f32_16x16x32_bf16 v[36:39], v[124:127], v[120:123], v[36:39]
	ds_read_b64_tr_b16 v[124:125], v202 offset:32
	ds_read_b64_tr_b16 v[126:127], v202 offset:4640
	s_waitcnt lgkmcnt(6)
	v_mfma_f32_16x16x32_bf16 v[64:67], v[128:131], v[104:107], v[64:67]
	v_mfma_f32_16x16x32_bf16 v[36:39], v[128:131], v[116:119], v[36:39]
	ds_read_b64_tr_b16 v[128:129], v202 offset:9248
	ds_read_b64_tr_b16 v[130:131], v202 offset:13856
	s_waitcnt lgkmcnt(6)
	v_mfma_f32_16x16x32_bf16 v[64:67], v[132:135], v[100:103], v[64:67]
	v_mfma_f32_16x16x32_bf16 v[36:39], v[132:135], v[112:115], v[36:39]
	ds_read_b64_tr_b16 v[132:133], v202 offset:18464
	ds_read_b64_tr_b16 v[134:135], v202 offset:23072
	s_waitcnt lgkmcnt(6)
	v_mfma_f32_16x16x32_bf16 v[64:67], v[136:139], v[92:95], v[64:67]
	v_mfma_f32_16x16x32_bf16 v[36:39], v[136:139], v[84:87], v[36:39]
	ds_read_b64_tr_b16 v[136:137], v202 offset:27680
	ds_read_b64_tr_b16 v[138:139], v202 offset:32288
	s_waitcnt lgkmcnt(6)
	v_mfma_f32_16x16x32_bf16 v[60:63], v[124:127], v[108:111], v[60:63]
	v_mfma_f32_16x16x32_bf16 v[32:35], v[124:127], v[120:123], v[32:35]
	ds_read_b64_tr_b16 v[124:125], v202 offset:64
	ds_read_b64_tr_b16 v[126:127], v202 offset:4672
	s_waitcnt lgkmcnt(6)
	v_mfma_f32_16x16x32_bf16 v[60:63], v[128:131], v[104:107], v[60:63]
	v_mfma_f32_16x16x32_bf16 v[32:35], v[128:131], v[116:119], v[32:35]
	ds_read_b64_tr_b16 v[128:129], v202 offset:9280
	ds_read_b64_tr_b16 v[130:131], v202 offset:13888
	s_waitcnt lgkmcnt(6)
	v_mfma_f32_16x16x32_bf16 v[60:63], v[132:135], v[100:103], v[60:63]
	v_mfma_f32_16x16x32_bf16 v[32:35], v[132:135], v[112:115], v[32:35]
	ds_read_b64_tr_b16 v[132:133], v202 offset:18496
	ds_read_b64_tr_b16 v[134:135], v202 offset:23104
	s_waitcnt lgkmcnt(6)
	v_mfma_f32_16x16x32_bf16 v[60:63], v[136:139], v[92:95], v[60:63]
	v_mfma_f32_16x16x32_bf16 v[32:35], v[136:139], v[84:87], v[32:35]
	ds_read_b64_tr_b16 v[136:137], v202 offset:27712
	ds_read_b64_tr_b16 v[138:139], v202 offset:32320
	s_waitcnt lgkmcnt(6)
	v_mfma_f32_16x16x32_bf16 v[68:71], v[124:127], v[108:111], v[68:71]
	v_mfma_f32_16x16x32_bf16 v[40:43], v[124:127], v[120:123], v[40:43]
	ds_read_b64_tr_b16 v[124:125], v202 offset:96
	ds_read_b64_tr_b16 v[126:127], v202 offset:4704
	s_waitcnt lgkmcnt(6)
	v_mfma_f32_16x16x32_bf16 v[68:71], v[128:131], v[104:107], v[68:71]
	v_mfma_f32_16x16x32_bf16 v[40:43], v[128:131], v[116:119], v[40:43]
	ds_read_b64_tr_b16 v[128:129], v202 offset:9312
	ds_read_b64_tr_b16 v[130:131], v202 offset:13920
	s_waitcnt lgkmcnt(6)
	v_mfma_f32_16x16x32_bf16 v[68:71], v[132:135], v[100:103], v[68:71]
	v_mfma_f32_16x16x32_bf16 v[40:43], v[132:135], v[112:115], v[40:43]
	ds_read_b64_tr_b16 v[132:133], v202 offset:18528
	ds_read_b64_tr_b16 v[134:135], v202 offset:23136
	s_waitcnt lgkmcnt(6)
; #define LAS __attribute__((address_space(3)))
; __device__ __forceinline__ void attn_unit(const bf16* proj, unsigned char* ws, LAS unsigned char* lds, int a) {
;     ...
; #pragma unroll
;         for (int dt = 0; dt < 8; ++dt)
; #pragma unroll
;             for (int tp = 0; tp < 4; ++tp) {
;                 const LAS unsigned char* p0 = VS + (32 * tp + 4 * fq + (fr >> 2)) * V_STRIDE + (16 * dt + 4 * (fr & 3)) * 2;
;                 const bf16x8 vf = tr_frag(p0, p0 + 16 * V_STRIDE);
;                 O[0][dt] = __builtin_amdgcn_mfma_f32_16x16x32_bf16(vf, pb[0][tp], O[0][dt], 0, 0, 0);
;                 O[1][dt] = __builtin_amdgcn_mfma_f32_16x16x32_bf16(vf, pb[1][tp], O[1][dt], 0, 0, 0);
;             }
	v_mfma_f32_16x16x32_bf16 v[68:71], v[136:139], v[92:95], v[68:71]
	v_mfma_f32_16x16x32_bf16 v[40:43], v[136:139], v[84:87], v[40:43]
	ds_read_b64_tr_b16 v[136:137], v202 offset:27744
	ds_read_b64_tr_b16 v[138:139], v202 offset:32352
	s_waitcnt lgkmcnt(6)
	v_mfma_f32_16x16x32_bf16 v[72:75], v[124:127], v[108:111], v[72:75]
	v_mfma_f32_16x16x32_bf16 v[44:47], v[124:127], v[120:123], v[44:47]
	ds_read_b64_tr_b16 v[124:125], v202 offset:128
	ds_read_b64_tr_b16 v[126:127], v202 offset:4736
	s_waitcnt lgkmcnt(6)
	v_mfma_f32_16x16x32_bf16 v[72:75], v[128:131], v[104:107], v[72:75]
	v_mfma_f32_16x16x32_bf16 v[44:47], v[128:131], v[116:119], v[44:47]
	ds_read_b64_tr_b16 v[128:129], v202 offset:9344
	ds_read_b64_tr_b16 v[130:131], v202 offset:13952
	s_waitcnt lgkmcnt(6)
	v_mfma_f32_16x16x32_bf16 v[72:75], v[132:135], v[100:103], v[72:75]
	v_mfma_f32_16x16x32_bf16 v[44:47], v[132:135], v[112:115], v[44:47]
	ds_read_b64_tr_b16 v[132:133], v202 offset:18560
	ds_read_b64_tr_b16 v[134:135], v202 offset:23168
	s_waitcnt lgkmcnt(6)
	v_mfma_f32_16x16x32_bf16 v[72:75], v[136:139], v[92:95], v[72:75]
	v_mfma_f32_16x16x32_bf16 v[44:47], v[136:139], v[84:87], v[44:47]
	ds_read_b64_tr_b16 v[136:137], v202 offset:27776
	ds_read_b64_tr_b16 v[138:139], v202 offset:32384
	s_waitcnt lgkmcnt(6)
	v_mfma_f32_16x16x32_bf16 v[76:79], v[124:127], v[108:111], v[76:79]
	v_mfma_f32_16x16x32_bf16 v[48:51], v[124:127], v[120:123], v[48:51]
	ds_read_b64_tr_b16 v[124:125], v202 offset:160
	ds_read_b64_tr_b16 v[126:127], v202 offset:4768
	s_waitcnt lgkmcnt(6)
	v_mfma_f32_16x16x32_bf16 v[76:79], v[128:131], v[104:107], v[76:79]
	v_mfma_f32_16x16x32_bf16 v[48:51], v[128:131], v[116:119], v[48:51]
	ds_read_b64_tr_b16 v[128:129], v202 offset:9376
	ds_read_b64_tr_b16 v[130:131], v202 offset:13984
	s_waitcnt lgkmcnt(6)
	v_mfma_f32_16x16x32_bf16 v[76:79], v[132:135], v[100:103], v[76:79]
	v_mfma_f32_16x16x32_bf16 v[48:51], v[132:135], v[112:115], v[48:51]
	ds_read_b64_tr_b16 v[132:133], v202 offset:18592
	ds_read_b64_tr_b16 v[134:135], v202 offset:23200
	s_waitcnt lgkmcnt(6)
	v_mfma_f32_16x16x32_bf16 v[76:79], v[136:139], v[92:95], v[76:79]
	v_mfma_f32_16x16x32_bf16 v[48:51], v[136:139], v[84:87], v[48:51]
	ds_read_b64_tr_b16 v[136:137], v202 offset:27808
	ds_read_b64_tr_b16 v[138:139], v202 offset:32416
	s_waitcnt lgkmcnt(6)
	v_mfma_f32_16x16x32_bf16 v[80:83], v[124:127], v[108:111], v[80:83]
	v_mfma_f32_16x16x32_bf16 v[52:55], v[124:127], v[120:123], v[52:55]
	ds_read_b64_tr_b16 v[124:125], v202 offset:192
	ds_read_b64_tr_b16 v[126:127], v202 offset:4800
	s_waitcnt lgkmcnt(6)
	v_mfma_f32_16x16x32_bf16 v[80:83], v[128:131], v[104:107], v[80:83]
	v_mfma_f32_16x16x32_bf16 v[52:55], v[128:131], v[116:119], v[52:55]
	ds_read_b64_tr_b16 v[128:129], v202 offset:9408
	ds_read_b64_tr_b16 v[130:131], v202 offset:14016
	s_waitcnt lgkmcnt(6)
	v_mfma_f32_16x16x32_bf16 v[80:83], v[132:135], v[100:103], v[80:83]
	v_mfma_f32_16x16x32_bf16 v[52:55], v[132:135], v[112:115], v[52:55]
	ds_read_b64_tr_b16 v[132:133], v202 offset:18624
	ds_read_b64_tr_b16 v[134:135], v202 offset:23232
	s_waitcnt lgkmcnt(6)
	v_mfma_f32_16x16x32_bf16 v[80:83], v[136:139], v[92:95], v[80:83]
	v_mfma_f32_16x16x32_bf16 v[52:55], v[136:139], v[84:87], v[52:55]
	ds_read_b64_tr_b16 v[136:137], v202 offset:27840
	ds_read_b64_tr_b16 v[138:139], v202 offset:32448
	s_waitcnt lgkmcnt(6)
	v_mfma_f32_16x16x32_bf16 v[88:91], v[124:127], v[108:111], v[88:91]
	v_mfma_f32_16x16x32_bf16 v[56:59], v[124:127], v[120:123], v[56:59]
	ds_read_b64_tr_b16 v[124:125], v202 offset:224
	ds_read_b64_tr_b16 v[126:127], v202 offset:4832
	s_waitcnt lgkmcnt(6)
	v_mfma_f32_16x16x32_bf16 v[88:91], v[128:131], v[104:107], v[88:91]
	v_mfma_f32_16x16x32_bf16 v[56:59], v[128:131], v[116:119], v[56:59]
	ds_read_b64_tr_b16 v[128:129], v202 offset:9440
	ds_read_b64_tr_b16 v[130:131], v202 offset:14048
	s_waitcnt lgkmcnt(6)
	v_mfma_f32_16x16x32_bf16 v[88:91], v[132:135], v[100:103], v[88:91]
	v_mfma_f32_16x16x32_bf16 v[56:59], v[132:135], v[112:115], v[56:59]
	ds_read_b64_tr_b16 v[132:133], v202 offset:18656
	ds_read_b64_tr_b16 v[134:135], v202 offset:23264
	s_waitcnt lgkmcnt(6)
	v_mfma_f32_16x16x32_bf16 v[88:91], v[136:139], v[92:95], v[88:91]
	v_mfma_f32_16x16x32_bf16 v[56:59], v[136:139], v[84:87], v[56:59]
	ds_read_b64_tr_b16 v[136:137], v202 offset:27872
	ds_read_b64_tr_b16 v[138:139], v202 offset:32480
	s_waitcnt lgkmcnt(6)
	v_mfma_f32_16x16x32_bf16 v[96:99], v[124:127], v[108:111], v[96:99]
	v_mfma_f32_16x16x32_bf16 v[108:111], v[124:127], v[120:123], v[144:147]
	s_waitcnt lgkmcnt(4)
	v_mfma_f32_16x16x32_bf16 v[96:99], v[128:131], v[104:107], v[96:99]
	v_mfma_f32_16x16x32_bf16 v[104:107], v[128:131], v[116:119], v[108:111]
	s_waitcnt lgkmcnt(2)
	v_mfma_f32_16x16x32_bf16 v[96:99], v[132:135], v[100:103], v[96:99]
	v_mfma_f32_16x16x32_bf16 v[100:103], v[132:135], v[112:115], v[104:107]
	s_waitcnt lgkmcnt(0)
	v_mfma_f32_16x16x32_bf16 v[96:99], v[136:139], v[92:95], v[96:99]
	v_mfma_f32_16x16x32_bf16 v[84:87], v[136:139], v[84:87], v[100:103]
	s_cbranch_vccnz .LBB0_614
	v_mov_b32_e32 v209, v207
	v_mov_b32_e32 v208, v148
	s_cmp_eq_u32 s51, 0
	s_cbranch_scc0 .LBB0_605
	s_branch .LBB0_606
